# HGRN pass C: next-item prefetch block moved from before the first elementwise part to after the item's first barrier (SCC preserved)
# speedup vs baseline: 1.0050x; 1.0029x over previous
; #define LAS __attribute__((address_space(3)))
; DI float h2f(unsigned short u) { return (float)__builtin_bit_cast(_Float16, u); }
; DI float flog(float x) { return __builtin_amdgcn_logf(x) * 0.6931471805599453f; }
; DI float sigmoidf_(float x) { return frcp(1.f + fexp(-x)); }
; DI void hgC_item(LAS unsigned char* lds, unsigned char* ws, unsigned char* ob, int item, const float* ng, int dummy, const unsigned (&lfr)[16], const unsigned (&qvr)[16], const u32x4 (&ivw)[2], const float* lbp) {
;     ...
;     float kk0[8], kk1[8], q0v[8], q1v[8], cs0[8], cs1[8];
;     {
;         const f32x2 lb2 = *(const f32x2*)(lbp + h * 128 + 2 * kp);
;         float run0 = 0.f, run1 = 0.f;
; #pragma unroll
;         for (int i = 0; i < 8; ++i) {
;             const float om0 = (1.f - lb2[0]) * sigmoidf_(-h2f((unsigned short)(lfr[i] & 0xffffu)));
;             const float om1 = (1.f - lb2[1]) * sigmoidf_(-h2f((unsigned short)(lfr[i] >> 16)));
;             kk0[i] = om0; kk1[i] = om1;
;             run0 += flog(1.f - om0); run1 += flog(1.f - om1);
;             cs0[i] = run0; cs1[i] = run1;
;             q0v[i] = bflo(qvr[i]); q1v[i] = bfhi(qvr[i]);
;         }
;         *(LAS f32x2*)(tot + tq * 128 + 2 * kp) = (f32x2){run0, run1};
;     }
;     hg_iv_store(VTs, ivw);
; #pragma unroll
;     for (int j = 0; j < 4; ++j) { const int id = tid + 512 * j; *(LAS u32x4*)(SS + (id >> 4) * HROW + (id & 15) * 16) = sreg[j]; }
;     __syncthreads();
;     {
;         float off0 = 0.f, off1 = 0.f, bref0 = 0.f, bref1 = 0.f;
.LBB0_1114:
	v_mul_f32_e32 v55, 0x3fb8aa3b, v55
	v_exp_f32_e32 v55, v55
	v_cvt_f32_f16_e32 v49, v30
	v_add_f32_e32 v48, 1.0, v54
	v_rcp_f32_e32 v60, v48
	v_add_f32_e32 v48, 1.0, v55
	v_rcp_f32_e32 v61, v48
	v_cvt_f32_f16_sdwa v30, v30 dst_sel:DWORD dst_unused:UNUSED_PAD src0_sel:WORD_1
	v_mul_f32_e32 v48, 0x3fb8aa3b, v49
	v_exp_f32_e32 v48, v48
	v_lshlrev_b32_e32 v54, 16, v31
	v_mul_f32_e32 v30, 0x3fb8aa3b, v30
	v_exp_f32_e32 v30, v30
	v_and_b32_e32 v55, 0xffff0000, v31
	v_add_f32_e32 v31, 1.0, v48
	v_rcp_f32_e32 v62, v31
	v_cvt_f32_f16_e32 v31, v28
	v_add_f32_e32 v30, 1.0, v30
	v_rcp_f32_e32 v63, v30
	v_cvt_f32_f16_sdwa v28, v28 dst_sel:DWORD dst_unused:UNUSED_PAD src0_sel:WORD_1
	v_mul_f32_e32 v30, 0x3fb8aa3b, v31
	v_exp_f32_e32 v30, v30
	v_lshlrev_b32_e32 v48, 16, v29
	v_mul_f32_e32 v28, 0x3fb8aa3b, v28
	v_exp_f32_e32 v28, v28
	v_and_b32_e32 v49, 0xffff0000, v29
	v_add_f32_e32 v29, 1.0, v30
	v_rcp_f32_e32 v64, v29
	v_cvt_f32_f16_e32 v29, v26
	v_cvt_f32_f16_sdwa v26, v26 dst_sel:DWORD dst_unused:UNUSED_PAD src0_sel:WORD_1
	v_add_f32_e32 v28, 1.0, v28
	v_rcp_f32_e32 v65, v28
	v_mul_f32_e32 v28, 0x3fb8aa3b, v29
	v_exp_f32_e32 v28, v28
	v_mul_f32_e32 v26, 0x3fb8aa3b, v26
	v_exp_f32_e32 v26, v26
	v_lshlrev_b32_e32 v30, 16, v27
	v_and_b32_e32 v31, 0xffff0000, v27
	v_add_f32_e32 v27, 1.0, v28
	v_rcp_f32_e32 v66, v27
	v_add_f32_e32 v26, 1.0, v26
	v_cvt_f32_f16_e32 v27, v56
	v_rcp_f32_e32 v67, v26
	v_cvt_f32_f16_sdwa v26, v56 dst_sel:DWORD dst_unused:UNUSED_PAD src0_sel:WORD_1
	v_lshlrev_b32_e32 v28, 16, v24
	v_mul_f32_e32 v27, 0x3fb8aa3b, v27
	v_exp_f32_e32 v27, v27
	v_mul_f32_e32 v26, 0x3fb8aa3b, v26
	v_exp_f32_e32 v26, v26
	v_and_b32_e32 v29, 0xffff0000, v24
	v_add_f32_e32 v24, 1.0, v27
	v_rcp_f32_e32 v56, v24
	v_add_f32_e32 v24, 1.0, v26
	v_rcp_f32_e32 v57, v24
	v_cvt_f32_f16_sdwa v24, v52 dst_sel:DWORD dst_unused:UNUSED_PAD src0_sel:WORD_1
	v_cvt_f32_f16_e32 v27, v52
	v_cvt_f32_f16_e32 v68, v25
	v_lshlrev_b32_e32 v26, 16, v53
	v_mul_f32_e32 v24, 0x3fb8aa3b, v24
	v_exp_f32_e32 v24, v24
	v_mul_f32_e32 v27, 0x3fb8aa3b, v27
	v_exp_f32_e32 v52, v27
	v_and_b32_e32 v27, 0xffff0000, v53
	v_add_f32_e32 v24, 1.0, v24
	v_rcp_f32_e32 v53, v24
	v_mul_f32_e32 v24, 0x3fb8aa3b, v68
	v_exp_f32_e32 v68, v24
	v_cvt_f32_f16_sdwa v69, v25 dst_sel:DWORD dst_unused:UNUSED_PAD src0_sel:WORD_1
	v_lshlrev_b32_e32 v24, 16, v51
	v_and_b32_e32 v25, 0xffff0000, v51
	v_add_f32_e32 v51, 1.0, v68
	v_mul_f32_e32 v68, 0x3fb8aa3b, v69
	v_exp_f32_e32 v69, v68
	v_cvt_f32_f16_e32 v72, v50
	v_cvt_f32_f16_sdwa v50, v50 dst_sel:DWORD dst_unused:UNUSED_PAD src0_sel:WORD_1
	v_rcp_f32_e32 v68, v51
	v_add_f32_e32 v51, 1.0, v69
	v_mul_f32_e32 v69, 0x3fb8aa3b, v72
	v_mul_f32_e32 v50, 0x3fb8aa3b, v50
	v_exp_f32_e32 v72, v69
	v_exp_f32_e32 v73, v50
	ds_write_b128 v115, v[4:7] offset:52224
	s_waitcnt vmcnt(0)
	v_pk_add_f32 v[4:5], v[58:59], 1.0 op_sel_hi:[1,0] neg_lo:[1,0] neg_hi:[1,0]
	v_rcp_f32_e32 v69, v51
	v_add_f32_e32 v50, 1.0, v72
	v_add_f32_e32 v51, 1.0, v73
	v_pk_mul_f32 v[72:73], v[4:5], v[60:61]
	v_pk_mul_f32 v[74:75], v[4:5], v[62:63]
	v_sub_f32_e32 v6, 1.0, v72
	v_sub_f32_e32 v7, 1.0, v73
	v_log_f32_e32 v6, v6
	v_log_f32_e32 v7, v7
	v_sub_f32_e32 v58, 1.0, v74
	v_sub_f32_e32 v59, 1.0, v75
	v_log_f32_e32 v58, v58
	v_log_f32_e32 v59, v59
	v_add_f32_e32 v52, 1.0, v52
	v_pk_mul_f32 v[64:65], v[4:5], v[64:65]
	v_rcp_f32_e32 v52, v52
	v_sub_f32_e32 v60, 1.0, v64
	v_log_f32_e32 v62, v60
	v_sub_f32_e32 v60, 1.0, v65
	v_pk_fma_f32 v[76:77], v[6:7], s[72:73], 0 op_sel_hi:[1,0,0]
	v_log_f32_e32 v63, v60
	v_pk_fma_f32 v[78:79], v[58:59], s[72:73], v[76:77] op_sel_hi:[1,0,1]
	v_pk_mul_f32 v[58:59], v[4:5], v[56:57]
	v_pk_mul_f32 v[52:53], v[4:5], v[52:53]
	v_sub_f32_e32 v6, 1.0, v58
	v_log_f32_e32 v56, v6
	v_sub_f32_e32 v6, 1.0, v59
	v_rcp_f32_e32 v50, v50
	v_rcp_f32_e32 v51, v51
	v_pk_mul_f32 v[60:61], v[4:5], v[66:67]
	v_log_f32_e32 v57, v6
	v_sub_f32_e32 v6, 1.0, v52
	v_sub_f32_e32 v66, 1.0, v60
	v_sub_f32_e32 v67, 1.0, v61
	v_pk_fma_f32 v[136:137], v[62:63], s[72:73], v[78:79] op_sel_hi:[1,0,1]
	v_log_f32_e32 v62, v6
	v_sub_f32_e32 v6, 1.0, v53
	v_log_f32_e32 v66, v66
	v_log_f32_e32 v67, v67
	v_log_f32_e32 v63, v6
	v_pk_mul_f32 v[6:7], v[4:5], v[68:69]
	v_pk_mul_f32 v[4:5], v[4:5], v[50:51]
	v_sub_f32_e32 v68, 1.0, v6
	v_log_f32_e32 v138, v68
	v_sub_f32_e32 v68, 1.0, v7
	v_log_f32_e32 v139, v68
	v_sub_f32_e32 v50, 1.0, v4
	v_sub_f32_e32 v51, 1.0, v5
	v_pk_fma_f32 v[66:67], v[66:67], s[72:73], v[136:137] op_sel_hi:[1,0,1]
	v_log_f32_e32 v50, v50
	v_log_f32_e32 v51, v51
	v_pk_fma_f32 v[68:69], v[56:57], s[72:73], v[66:67] op_sel_hi:[1,0,1]
	s_ashr_i32 s90, s97, 2
	v_pk_fma_f32 v[62:63], v[62:63], s[72:73], v[68:69] op_sel_hi:[1,0,1]
	s_lshl_b32 s68, s90, 5
	v_pk_fma_f32 v[56:57], v[138:139], s[72:73], v[62:63] op_sel_hi:[1,0,1]
	s_cmp_lt_i32 s90, 0
	v_pk_fma_f32 v[50:51], v[50:51], s[72:73], v[56:57] op_sel_hi:[1,0,1]
	ds_write_b64 v104, v[50:51]
	ds_write_b128 v116, v[0:3] offset:52224
	v_add_u32_e32 v0, v105, v106
	v_add_u32_e32 v1, v105, v107
	ds_write_b128 v0, v[8:11]
	ds_write_b128 v1, v[12:15]
	ds_write_b128 v0, v[16:19] offset:17408
	ds_write_b128 v117, v[20:23]
	s_waitcnt lgkmcnt(0)
	s_barrier
	s_cselect_b32 s32, 1, 0
	s_and_b64 vcc, exec, s[76:77]
	s_cbranch_vccnz .Lp9_pfskip
; #define LAS __attribute__((address_space(3)))
; DI unsigned pk2(float lo, float hi) { f32x2 v = {lo, hi}; bf2_t b = __builtin_convertvector(v, bf2_t); return __builtin_bit_cast(unsigned, b); }
; DI float fexp(float x) { return __builtin_amdgcn_exp2f(x * 1.4426950408889634f); }
; DI void hgC_load(unsigned char* ws, int item, unsigned (&lf)[16], unsigned (&qv)[16], u32x4 (&ivw)[2]) {
;     const int tid = threadIdx.x, b = item >> 10, h = (item >> 6) & 15, c = item & 63, t0 = b * SEQ + c * 64, kp = tid & 63, tq = tid >> 6;
;     const bf16_t* LOGF = (const bf16_t*)(ws + WS_LOGF);
;     const bf16_t* Q2 = (const bf16_t*)(ws + WS_Q2);
; #pragma unroll
;     for (int i = 0; i < 8; ++i) { const size_t o = (size_t)(t0 + tq * 8 + i) * DM + h * 128 + 2 * kp; lf[i] = *(const unsigned*)(LOGF + o); qv[i] = *(const unsigned*)(Q2 + o); }
;     hg_iv_load((const bf16_t*)(ws + WS_IV), item, ivw);
; DI void hgC_item(LAS unsigned char* lds, unsigned char* ws, unsigned char* ob, int item, const float* ng, int dummy, const unsigned (&lfr)[16], const unsigned (&qvr)[16], const u32x4 (&ivw)[2], const float* lbp) {
;     ...
;     {
;         float off0 = 0.f, off1 = 0.f, bref0 = 0.f, bref1 = 0.f;
; #pragma unroll
;         for (int q = 0; q < 8; ++q) {
;             const f32x2 tv = *(LAS f32x2*)(tot + q * 128 + 2 * kp);
;             if (q < tq) { off0 += tv[0]; off1 += tv[1]; }
;             if (q < 4) { bref0 += tv[0]; bref1 += tv[1]; }
;         }
; #pragma unroll
;         for (int i = 0; i < 8; ++i) {
;             const int t = tq * 8 + i;
;             const float bb0 = off0 + cs0[i], bb1 = off1 + cs1[i];
;             const float qi0 = q0v[i] * fexp(bb0), qi1 = q1v[i] * fexp(bb1);
;             const float qa0 = q0v[i] * fexp(fminf(bb0 - bref0, 80.f)), qa1 = q1v[i] * fexp(fminf(bb1 - bref1, 80.f));
;             const float ka0 = kk0[i] * fexp(fminf(bref0 - bb0, 80.f)), ka1 = kk1[i] * fexp(fminf(bref1 - bb1, 80.f));
;             *(LAS unsigned*)(QI + t * HROW + kp * 4) = pk2(qi0, qi1);
;             *(LAS unsigned*)(QA + t * HROW + kp * 4) = pk2(qa0, qa1);
;             *(LAS unsigned*)(KA + t * HROW + kp * 4) = pk2(ka0, ka1);
;         }
;     }
	s_lshl_b32 s56, s74, 2
	s_lshl_b32 s57, s74, 6
	s_and_b32 s56, s56, 0xfffff000
	s_and_b32 s57, s57, 0xfc0
	s_or_b32 s56, s56, s57
	v_readlane_b32 s57, v254, 3
	s_nop 0
	s_lshl_b32 s57, s57, 3
	s_add_i32 s56, s56, s57
	s_lshl_b32 s56, s56, 12
	s_lshl_b32 s57, s74, 1
	s_and_b32 s57, s57, 0x780
	s_lshl_b32 s57, s57, 1
	s_add_u32 s56, s56, s57
	s_add_u32 s98, s64, s56
	s_addc_u32 s99, s65, 0
	s_add_u32 s100, s66, s56
	s_addc_u32 s101, s67, 0
	v_lshlrev_b32_e32 v148, 1, v98
	global_load_dword v120, v148, s[98:99]
	global_load_dword v121, v148, s[100:101]
	s_add_u32 s98, s98, 0x1000
	s_addc_u32 s99, s99, 0
	s_add_u32 s100, s100, 0x1000
	s_addc_u32 s101, s101, 0
	global_load_dword v122, v148, s[98:99]
	global_load_dword v123, v148, s[100:101]
	s_add_u32 s98, s98, 0x1000
	s_addc_u32 s99, s99, 0
	s_add_u32 s100, s100, 0x1000
	s_addc_u32 s101, s101, 0
	global_load_dword v124, v148, s[98:99]
	global_load_dword v125, v148, s[100:101]
	s_add_u32 s98, s98, 0x1000
	s_addc_u32 s99, s99, 0
	s_add_u32 s100, s100, 0x1000
	s_addc_u32 s101, s101, 0
	global_load_dword v126, v148, s[98:99]
	global_load_dword v127, v148, s[100:101]
	s_add_u32 s98, s98, 0x1000
	s_addc_u32 s99, s99, 0
	s_add_u32 s100, s100, 0x1000
	s_addc_u32 s101, s101, 0
	global_load_dword v128, v148, s[98:99]
	global_load_dword v129, v148, s[100:101]
	s_add_u32 s98, s98, 0x1000
	s_addc_u32 s99, s99, 0
	s_add_u32 s100, s100, 0x1000
	s_addc_u32 s101, s101, 0
	global_load_dword v130, v148, s[98:99]
	global_load_dword v131, v148, s[100:101]
	s_add_u32 s98, s98, 0x1000
	s_addc_u32 s99, s99, 0
	s_add_u32 s100, s100, 0x1000
	s_addc_u32 s101, s101, 0
	global_load_dword v132, v148, s[98:99]
	global_load_dword v133, v148, s[100:101]
	s_add_u32 s98, s98, 0x1000
	s_addc_u32 s99, s99, 0
	s_add_u32 s100, s100, 0x1000
	s_addc_u32 s101, s101, 0
	global_load_dword v134, v148, s[98:99]
	global_load_dword v135, v148, s[100:101]
	s_mov_b32 s56, s74
	s_ashr_i32 s57, s74, 31
	s_lshl_b64 s[56:57], s[56:57], 14
	v_lshl_add_u64 v[148:149], v[82:83], 0, s[56:57]
	v_add_co_u32_e32 v150, vcc, 0x2000, v148
	s_nop 1
	v_addc_co_u32_e32 v151, vcc, 0, v149, vcc
	global_load_dwordx4 v[32:35], v[148:149], off
	global_load_dwordx4 v[36:39], v[150:151], off
.Lp9_pfskip:
	s_cmp_lg_u32 s32, 0
	ds_read2st64_b64 v[8:11], v103 offset1:1
	ds_read2st64_b64 v[12:15], v103 offset0:2 offset1:3
	v_lshlrev_b32_e32 v2, 16, v71
	v_and_b32_e32 v3, 0xffff0000, v71
	v_lshlrev_b32_e32 v0, 16, v70
	s_waitcnt lgkmcnt(1)
	v_add_f32_e32 v1, 0, v8
	v_cndmask_b32_e64 v16, v1, 0, s[4:5]
	v_add_f32_e32 v8, 0, v9
	v_add_f32_e32 v17, v10, v16
	v_cndmask_b32_e64 v9, v8, 0, s[4:5]
	v_cndmask_b32_e64 v16, v16, v17, s[6:7]
	v_add_f32_e32 v18, v11, v9
	v_add_f32_e32 v1, v1, v10
	s_waitcnt lgkmcnt(0)
	v_add_f32_e32 v10, v12, v16
	v_cndmask_b32_e64 v9, v9, v18, s[6:7]
	v_cndmask_b32_e64 v10, v16, v10, s[8:9]
	ds_read2st64_b64 v[16:19], v103 offset0:4 offset1:5
	v_add_f32_e32 v8, v8, v11
	v_add_f32_e32 v11, v13, v9
	v_cndmask_b32_e64 v20, v9, v11, s[8:9]
	v_add_f32_e32 v11, v1, v12
	v_add_f32_e32 v9, v8, v13
	v_add_f32_e32 v1, v14, v10
	v_add_f32_e32 v8, v15, v20
	v_cndmask_b32_e64 v8, v20, v8, s[10:11]
	v_cndmask_b32_e64 v1, v10, v1, s[10:11]
	ds_read2st64_b64 v[20:23], v103 offset0:6 offset1:7
	s_waitcnt lgkmcnt(1)
	v_add_f32_e32 v10, v16, v1
	v_add_f32_e32 v12, v17, v8
	v_cndmask_b32_e64 v8, v8, v12, s[12:13]
	v_cndmask_b32_e64 v1, v1, v10, s[12:13]
	v_add_f32_e32 v10, v18, v1
	v_add_f32_e32 v12, v19, v8
	v_cndmask_b32_e64 v8, v8, v12, s[14:15]
	v_cndmask_b32_e64 v1, v1, v10, s[14:15]
	s_waitcnt lgkmcnt(0)
	v_add_f32_e32 v10, v20, v1
	v_add_f32_e32 v12, v21, v8
	v_cndmask_b32_e64 v8, v8, v12, s[16:17]
	v_cndmask_b32_e64 v1, v1, v10, s[16:17]
	v_add_f32_e32 v10, v22, v1
	v_add_f32_e32 v12, v23, v8
	v_cndmask_b32_e64 v8, v8, v12, s[18:19]
	v_cndmask_b32_e64 v10, v1, v10, s[18:19]
	v_mov_b32_e32 v12, v76
	v_mov_b32_e32 v13, v14
	v_pk_add_f32 v[12:13], v[12:13], v[10:11]
	v_mov_b32_e32 v14, v77
	v_pk_add_f32 v[14:15], v[14:15], v[8:9]
	v_mul_f32_e32 v1, 0x3fb8aa3b, v12
	v_exp_f32_e32 v16, v1
	v_mul_f32_e32 v1, 0x3fb8aa3b, v14
	v_exp_f32_e32 v17, v1
	v_sub_f32_e32 v1, v12, v13
	v_min_f32_e32 v1, 0x42a00000, v1
	v_mul_f32_e32 v1, 0x3fb8aa3b, v1
	v_exp_f32_e32 v18, v1
	v_sub_f32_e32 v1, v14, v15
	v_min_f32_e32 v1, 0x42a00000, v1
	v_mul_f32_e32 v1, 0x3fb8aa3b, v1
	v_exp_f32_e32 v19, v1
	v_sub_f32_e32 v1, v13, v12
	v_min_f32_e32 v1, 0x42a00000, v1
	v_pk_mul_f32 v[16:17], v[16:17], v[54:55]
	v_pk_mul_f32 v[18:19], v[18:19], v[54:55]
	v_add_f32_e32 v12, v78, v10
	v_mul_f32_e32 v1, 0x3fb8aa3b, v1
	v_cvt_pk_bf16_f32 v9, v16, v17
	v_cvt_pk_bf16_f32 v11, v18, v19
	v_mul_f32_e32 v16, 0x3fb8aa3b, v12
	v_sub_f32_e32 v18, v12, v13
	v_sub_f32_e32 v12, v13, v12
	v_exp_f32_e32 v20, v1
	v_sub_f32_e32 v1, v15, v14
	v_add_f32_e32 v14, v79, v8
	v_min_f32_e32 v12, 0x42a00000, v12
	v_sub_f32_e32 v19, v14, v15
	v_mul_f32_e32 v12, 0x3fb8aa3b, v12
	v_min_f32_e32 v1, 0x42a00000, v1
	v_mul_f32_e32 v17, 0x3fb8aa3b, v14
	v_min_f32_e32 v18, 0x42a00000, v18
	v_min_f32_e32 v19, 0x42a00000, v19
	v_exp_f32_e32 v22, v12
	v_sub_f32_e32 v12, v15, v14
	v_mul_f32_e32 v1, 0x3fb8aa3b, v1
	v_exp_f32_e32 v16, v16
	v_exp_f32_e32 v17, v17
	v_mul_f32_e32 v18, 0x3fb8aa3b, v18
	v_mul_f32_e32 v19, 0x3fb8aa3b, v19
	v_min_f32_e32 v12, 0x42a00000, v12
	v_exp_f32_e32 v21, v1
	v_exp_f32_e32 v18, v18
	v_exp_f32_e32 v19, v19
	v_mul_f32_e32 v12, 0x3fb8aa3b, v12
	v_exp_f32_e32 v23, v12
	v_pk_mul_f32 v[16:17], v[16:17], v[48:49]
	v_pk_mul_f32 v[20:21], v[72:73], v[20:21]
	v_pk_mul_f32 v[18:19], v[18:19], v[48:49]
	v_cvt_pk_bf16_f32 v14, v16, v17
	v_cvt_pk_bf16_f32 v12, v20, v21
	v_pk_mul_f32 v[20:21], v[74:75], v[22:23]
; #define LAS __attribute__((address_space(3)))
; DI unsigned pk2(float lo, float hi) { f32x2 v = {lo, hi}; bf2_t b = __builtin_convertvector(v, bf2_t); return __builtin_bit_cast(unsigned, b); }
; DI float fexp(float x) { return __builtin_amdgcn_exp2f(x * 1.4426950408889634f); }
; DI void hgC_item(LAS unsigned char* lds, unsigned char* ws, unsigned char* ob, int item, const float* ng, int dummy, const unsigned (&lfr)[16], const unsigned (&qvr)[16], const u32x4 (&ivw)[2], const float* lbp) {
;     ...
; #pragma unroll
;         for (int i = 0; i < 8; ++i) {
;             const int t = tq * 8 + i;
;             const float bb0 = off0 + cs0[i], bb1 = off1 + cs1[i];
;             const float qi0 = q0v[i] * fexp(bb0), qi1 = q1v[i] * fexp(bb1);
;             const float qa0 = q0v[i] * fexp(fminf(bb0 - bref0, 80.f)), qa1 = q1v[i] * fexp(fminf(bb1 - bref1, 80.f));
;             const float ka0 = kk0[i] * fexp(fminf(bref0 - bb0, 80.f)), ka1 = kk1[i] * fexp(fminf(bref1 - bb1, 80.f));
;             *(LAS unsigned*)(QI + t * HROW + kp * 4) = pk2(qi0, qi1);
;             *(LAS unsigned*)(QA + t * HROW + kp * 4) = pk2(qa0, qa1);
;             *(LAS unsigned*)(KA + t * HROW + kp * 4) = pk2(ka0, ka1);
;         }
	ds_write2_b32 v118, v9, v14 offset1:68
	v_cvt_pk_bf16_f32 v9, v18, v19
	v_add_u32_e32 v14, 0x4400, v118
	ds_write2_b32 v14, v11, v9 offset1:68
	v_cvt_pk_bf16_f32 v9, v20, v21
	v_add_f32_e32 v20, v136, v10
	v_add_f32_e32 v21, v137, v8
	v_sub_f32_e32 v18, v20, v13
	v_sub_f32_e32 v19, v21, v15
	v_min_f32_e32 v18, 0x42a00000, v18
	v_min_f32_e32 v19, 0x42a00000, v19
	v_mul_f32_e32 v18, 0x3fb8aa3b, v18
	v_mul_f32_e32 v19, 0x3fb8aa3b, v19
	v_mul_f32_e32 v16, 0x3fb8aa3b, v20
	v_mul_f32_e32 v17, 0x3fb8aa3b, v21
	v_exp_f32_e32 v18, v18
	v_exp_f32_e32 v19, v19
	v_exp_f32_e32 v16, v16
	v_exp_f32_e32 v17, v17
	v_add_u32_e32 v11, 0x8800, v118
	v_pk_mul_f32 v[18:19], v[18:19], v[30:31]
	v_add_f32_e32 v22, v66, v10
	v_add_f32_e32 v23, v67, v8
	ds_write2_b32 v11, v12, v9 offset1:68
	v_pk_mul_f32 v[16:17], v[16:17], v[30:31]
	v_cvt_pk_bf16_f32 v12, v18, v19
	v_sub_f32_e32 v18, v22, v13
	v_sub_f32_e32 v19, v23, v15
	v_cvt_pk_bf16_f32 v9, v16, v17
	v_mul_f32_e32 v16, 0x3fb8aa3b, v22
	v_mul_f32_e32 v17, 0x3fb8aa3b, v23
	v_min_f32_e32 v18, 0x42a00000, v18
	v_min_f32_e32 v19, 0x42a00000, v19
	v_exp_f32_e32 v16, v16
	v_exp_f32_e32 v17, v17
	v_mul_f32_e32 v18, 0x3fb8aa3b, v18
	v_mul_f32_e32 v19, 0x3fb8aa3b, v19
	v_exp_f32_e32 v18, v18
	v_exp_f32_e32 v19, v19
	v_sub_f32_e32 v20, v13, v20
	v_sub_f32_e32 v21, v15, v21
	v_min_f32_e32 v20, 0x42a00000, v20
	v_min_f32_e32 v21, 0x42a00000, v21
	v_sub_f32_e32 v22, v13, v22
	v_sub_f32_e32 v23, v15, v23
	v_pk_mul_f32 v[16:17], v[16:17], v[28:29]
	v_mul_f32_e32 v20, 0x3fb8aa3b, v20
	v_mul_f32_e32 v21, 0x3fb8aa3b, v21
	v_min_f32_e32 v22, 0x42a00000, v22
	v_min_f32_e32 v23, 0x42a00000, v23
	v_pk_mul_f32 v[18:19], v[18:19], v[28:29]
	v_cvt_pk_bf16_f32 v16, v16, v17
	v_exp_f32_e32 v20, v20
	v_exp_f32_e32 v21, v21
	v_mul_f32_e32 v22, 0x3fb8aa3b, v22
	v_mul_f32_e32 v23, 0x3fb8aa3b, v23
	ds_write2_b32 v118, v9, v16 offset0:136 offset1:204
	v_cvt_pk_bf16_f32 v9, v18, v19
	v_exp_f32_e32 v22, v22
	v_exp_f32_e32 v23, v23
	ds_write2_b32 v14, v12, v9 offset0:136 offset1:204
	v_add_f32_e32 v12, v68, v10
	v_add_f32_e32 v14, v69, v8
	v_sub_f32_e32 v18, v12, v13
	v_sub_f32_e32 v19, v14, v15
	v_mul_f32_e32 v16, 0x3fb8aa3b, v12
	v_min_f32_e32 v18, 0x42a00000, v18
	v_min_f32_e32 v19, 0x42a00000, v19
	v_sub_f32_e32 v12, v13, v12
	v_pk_mul_f32 v[20:21], v[64:65], v[20:21]
	v_mul_f32_e32 v17, 0x3fb8aa3b, v14
	v_mul_f32_e32 v18, 0x3fb8aa3b, v18
	v_mul_f32_e32 v19, 0x3fb8aa3b, v19
	v_min_f32_e32 v12, 0x42a00000, v12
	v_cvt_pk_bf16_f32 v30, v20, v21
	v_pk_mul_f32 v[20:21], v[60:61], v[22:23]
	v_exp_f32_e32 v16, v16
	v_exp_f32_e32 v17, v17
	v_exp_f32_e32 v18, v18
	v_exp_f32_e32 v19, v19
	v_mul_f32_e32 v12, 0x3fb8aa3b, v12
	v_cvt_pk_bf16_f32 v9, v20, v21
	v_exp_f32_e32 v20, v12
	v_sub_f32_e32 v12, v15, v14
	v_min_f32_e32 v12, 0x42a00000, v12
	v_mul_f32_e32 v12, 0x3fb8aa3b, v12
	v_exp_f32_e32 v21, v12
	v_pk_mul_f32 v[16:17], v[16:17], v[26:27]
	v_pk_mul_f32 v[18:19], v[18:19], v[26:27]
	v_add_f32_e32 v12, v62, v10
	ds_write2_b32 v11, v30, v9 offset0:136 offset1:204
	v_cvt_pk_bf16_f32 v9, v16, v17
	v_cvt_pk_bf16_f32 v11, v18, v19
	v_mul_f32_e32 v16, 0x3fb8aa3b, v12
	v_sub_f32_e32 v18, v12, v13
	v_sub_f32_e32 v12, v13, v12
	v_min_f32_e32 v12, 0x42a00000, v12
	v_add_f32_e32 v14, v63, v8
	v_mul_f32_e32 v12, 0x3fb8aa3b, v12
	v_sub_f32_e32 v19, v14, v15
	v_exp_f32_e32 v22, v12
	v_sub_f32_e32 v12, v15, v14
	v_mul_f32_e32 v17, 0x3fb8aa3b, v14
	v_min_f32_e32 v18, 0x42a00000, v18
	v_min_f32_e32 v19, 0x42a00000, v19
	v_min_f32_e32 v12, 0x42a00000, v12
	v_exp_f32_e32 v16, v16
	v_exp_f32_e32 v17, v17
	v_mul_f32_e32 v18, 0x3fb8aa3b, v18
	v_mul_f32_e32 v19, 0x3fb8aa3b, v19
	v_mul_f32_e32 v12, 0x3fb8aa3b, v12
	v_exp_f32_e32 v18, v18
	v_exp_f32_e32 v19, v19
	v_exp_f32_e32 v23, v12
	v_pk_mul_f32 v[20:21], v[58:59], v[20:21]
	v_pk_mul_f32 v[16:17], v[16:17], v[24:25]
	v_cvt_pk_bf16_f32 v12, v20, v21
	v_pk_mul_f32 v[18:19], v[18:19], v[24:25]
	v_pk_mul_f32 v[20:21], v[52:53], v[22:23]
	v_cvt_pk_bf16_f32 v14, v16, v17
	v_add_u32_e32 v22, 0x400, v118
	ds_write2_b32 v22, v9, v14 offset0:16 offset1:84
	v_cvt_pk_bf16_f32 v9, v18, v19
	v_add_u32_e32 v14, 0x4800, v118
	ds_write2_b32 v14, v11, v9 offset0:16 offset1:84
	v_add_f32_e32 v11, v56, v10
	v_cvt_pk_bf16_f32 v9, v20, v21
	v_add_f32_e32 v21, v57, v8
	v_mul_f32_e32 v16, 0x3fb8aa3b, v11
	v_sub_f32_e32 v18, v11, v13
	v_sub_f32_e32 v11, v13, v11
	v_sub_f32_e32 v19, v21, v15
	v_min_f32_e32 v11, 0x42a00000, v11
	v_min_f32_e32 v18, 0x42a00000, v18
	v_min_f32_e32 v19, 0x42a00000, v19
	v_mul_f32_e32 v11, 0x3fb8aa3b, v11
	v_mul_f32_e32 v17, 0x3fb8aa3b, v21
	v_mul_f32_e32 v18, 0x3fb8aa3b, v18
	v_mul_f32_e32 v19, 0x3fb8aa3b, v19
	v_exp_f32_e32 v20, v11
	v_sub_f32_e32 v11, v15, v21
	v_exp_f32_e32 v16, v16
	v_exp_f32_e32 v17, v17
	v_exp_f32_e32 v18, v18
	v_exp_f32_e32 v19, v19
	v_min_f32_e32 v11, 0x42a00000, v11
	v_mul_f32_e32 v11, 0x3fb8aa3b, v11
	v_add_u32_e32 v23, 0x8c00, v118
	v_exp_f32_e32 v21, v11
	v_add_f32_e32 v10, v50, v10
	v_add_f32_e32 v11, v51, v8
	ds_write2_b32 v23, v12, v9 offset0:16 offset1:84
	v_sub_f32_e32 v8, v10, v13
	v_sub_f32_e32 v9, v11, v15
	v_pk_mul_f32 v[16:17], v[16:17], v[2:3]
	v_pk_mul_f32 v[2:3], v[18:19], v[2:3]
	v_min_f32_e32 v8, 0x42a00000, v8
	v_min_f32_e32 v9, 0x42a00000, v9
	v_cvt_pk_bf16_f32 v12, v16, v17
	v_cvt_pk_bf16_f32 v16, v2, v3
	v_mul_f32_e32 v2, 0x3fb8aa3b, v10
	v_mul_f32_e32 v3, 0x3fb8aa3b, v11
	v_mul_f32_e32 v8, 0x3fb8aa3b, v8
	v_mul_f32_e32 v9, 0x3fb8aa3b, v9
	v_sub_f32_e32 v10, v13, v10
	v_sub_f32_e32 v11, v15, v11
	v_exp_f32_e32 v2, v2
	v_exp_f32_e32 v3, v3
	v_exp_f32_e32 v8, v8
	v_exp_f32_e32 v9, v9
	v_min_f32_e32 v10, 0x42a00000, v10
	v_min_f32_e32 v11, 0x42a00000, v11
	v_mul_f32_e32 v10, 0x3fb8aa3b, v10
	v_mul_f32_e32 v11, 0x3fb8aa3b, v11
	v_exp_f32_e32 v10, v10
	v_exp_f32_e32 v11, v11
	v_and_b32_e32 v1, 0xffff0000, v70
	v_pk_mul_f32 v[2:3], v[2:3], v[0:1]
	v_pk_mul_f32 v[0:1], v[8:9], v[0:1]
	v_pk_mul_f32 v[6:7], v[6:7], v[20:21]
	v_cvt_pk_bf16_f32 v0, v0, v1
	v_pk_mul_f32 v[4:5], v[4:5], v[10:11]
	ds_write2_b32 v14, v16, v0 offset0:152 offset1:220
	v_lshl_or_b32 v16, s75, 5, v100
	v_cvt_pk_bf16_f32 v6, v6, v7
	v_cvt_pk_bf16_f32 v2, v2, v3
	v_cvt_pk_bf16_f32 v0, v4, v5
	v_mad_u32_u24 v30, v16, s96, v109
	ds_write2_b32 v22, v12, v2 offset0:152 offset1:220
	ds_write2_b32 v23, v6, v0 offset0:152 offset1:220
	s_waitcnt lgkmcnt(0)
	s_barrier
; #define LAS __attribute__((address_space(3)))
; DI void hgC_item(LAS unsigned char* lds, unsigned char* ws, unsigned char* ob, int item, const float* ng, int dummy, const unsigned (&lfr)[16], const unsigned (&qvr)[16], const u32x4 (&ivw)[2], const float* lbp) {
;     ...
;     f32x16 acc;
; #pragma unroll
;     for (int i = 0; i < 16; ++i) acc[i] = 0.f;
;     {
;         const LAS unsigned char* qp = QI + (32 * tb + r) * HROW + 16 * h2;
; #pragma unroll
;         for (int ks = 0; ks < 8; ++ks) {
;             const bf16x8 bq = *(const LAS bf16x8*)(qp + 32 * ks);
;             const bf16x8 sa = *(const LAS bf16x8*)(SS + (32 * vb + r) * HROW + 16 * h2 + 32 * ks);
;             acc = __builtin_amdgcn_mfma_f32_32x32x16_bf16(sa, bq, acc, 0, 0, 0);
;         }
;     }
;     for (int sb = 0; sb <= tb; ++sb) {
;         f32x16 AT;
; #pragma unroll
;         for (int i = 0; i < 16; ++i) AT[i] = 0.f;
;         const LAS unsigned char* kp = KA + (32 * sb + r) * HROW + 16 * h2;
;         const LAS unsigned char* qp = QA + (32 * tb + r) * HROW + 16 * h2;
; #pragma unroll
;         for (int ks = 0; ks < 8; ++ks) {
;             const bf16x8 a = *(const LAS bf16x8*)(kp + 32 * ks);
;             const bf16x8 bq = *(const LAS bf16x8*)(qp + 32 * ks);
	ds_read_b128 v[0:3], v30
	v_or_b32_e32 v136, s68, v100
	v_mul_lo_u32 v17, v136, s96
	v_add_u32_e32 v93, 0, v17
	v_add_u32_e32 v31, v93, v108
	ds_read_b128 v[4:7], v31
	ds_read_b128 v[18:21], v31 offset:32
	ds_read_b128 v[22:25], v30 offset:32
	s_waitcnt lgkmcnt(2)
	v_mfma_f32_32x32x16_bf16 v[0:15], v[0:3], v[4:7], 0
	s_waitcnt lgkmcnt(0)
	v_mfma_f32_32x32x16_bf16 v[0:15], v[22:25], v[18:21], v[0:15]
	ds_read_b128 v[18:21], v30 offset:64
	ds_read_b128 v[22:25], v31 offset:64
	ds_read_b128 v[26:29], v31 offset:96
	ds_read_b128 v[48:51], v30 offset:96
	s_waitcnt lgkmcnt(2)
	v_mfma_f32_32x32x16_bf16 v[0:15], v[18:21], v[22:25], v[0:15]
	s_waitcnt lgkmcnt(0)
	v_mfma_f32_32x32x16_bf16 v[0:15], v[48:51], v[26:29], v[0:15]
	ds_read_b128 v[18:21], v30 offset:128
	ds_read_b128 v[22:25], v31 offset:128
	ds_read_b128 v[26:29], v31 offset:160
	ds_read_b128 v[48:51], v30 offset:160
	s_waitcnt lgkmcnt(2)
	v_mfma_f32_32x32x16_bf16 v[0:15], v[18:21], v[22:25], v[0:15]
	s_waitcnt lgkmcnt(0)
	v_mfma_f32_32x32x16_bf16 v[0:15], v[48:51], v[26:29], v[0:15]
	ds_read_b128 v[18:21], v30 offset:192
	ds_read_b128 v[22:25], v31 offset:192
	ds_read_b128 v[26:29], v31 offset:224
	ds_read_b128 v[48:51], v30 offset:224
	s_waitcnt lgkmcnt(2)
	v_mfma_f32_32x32x16_bf16 v[0:15], v[18:21], v[22:25], v[0:15]
	s_waitcnt lgkmcnt(0)
	v_mfma_f32_32x32x16_bf16 v[0:15], v[48:51], v[26:29], v[0:15]
	s_cbranch_scc1 .LBB0_1122
	v_add_u32_e32 v17, v88, v17
	ds_read_b128 v[76:79], v17 offset:17408
	ds_read_b128 v[72:75], v17 offset:17440
	ds_read_b128 v[68:71], v17 offset:17472
	ds_read_b128 v[64:67], v17 offset:17504
	ds_read_b128 v[60:63], v17 offset:17536
	ds_read_b128 v[56:59], v17 offset:17568
	ds_read_b128 v[52:55], v17 offset:17600
	ds_read_b128 v[48:51], v17 offset:17632
	s_cmp_lt_u32 s97, 4
	v_mul_u32_u24_e32 v137, 0x90, v16
	s_cbranch_scc1 .LBB0_1120
	v_add_u32_e32 v138, v113, v137
	v_mov_b32_e32 v139, v114
	s_mov_b32 s97, s90
